# RG-LRU pass-0 loop: 16 x-column loads per iteration use scalar row base + precomputed lane offsets instead of 16 v_mad_i64_i32; on v094
# baseline (speedup 1.0000x reference)
; #define FIN(k) ((const float*)ptab(F.tab, (k)))
; __device__ __forceinline__ void lru_item(Frame& F, int l, int item) {
;     ...
;         for (int n = 0; n < 2; ++n) { const int ch = l * RW + g * 64 + hf * 32 + 16 * n + r; ba[n] = FIN(I_BGA)[ch]; bx[n] = FIN(I_BGX)[ch];
;             const float z = -FIN(I_LRULAM)[ch]; sp8[n] = 8.f * (fmaxf(z, 0.f) + log1pf(__expf(-fabsf(z)))); }
.LBB0_466:
	s_waitcnt vmcnt(3)
	v_max_f32_e64 v39, -v38, -v38
	v_mul_f32_e64 v38, |v38|, s46
	v_max_f32_e32 v41, 0, v39
	v_exp_f32_e32 v39, v38
	s_ashr_i32 s13, s12, 31
	s_lshl_b64 s[14:15], s[12:13], 15
	v_mov_b32_e32 v38, 1.0
	v_add_f32_e32 v50, 1.0, v39
	v_add_f32_e32 v40, -1.0, v50
	v_sub_f32_e32 v42, v40, v50
	v_add_f32_e32 v42, 1.0, v42
	v_sub_f32_e32 v40, v39, v40
	v_add_f32_e32 v51, v40, v42
	s_waitcnt vmcnt(0)
	v_max_f32_e64 v40, -v35, -v35
	v_mul_f32_e64 v35, |v35|, s46
	v_exp_f32_e32 v35, v35
	v_cvt_f64_f32_e32 v[42:43], v50
	v_frexp_exp_i32_f64_e32 v53, v[42:43]
	v_frexp_mant_f32_e32 v52, v50
	v_add_f32_e32 v61, 1.0, v35
	v_add_f32_e32 v42, -1.0, v61
	v_sub_f32_e32 v43, v42, v61
	v_add_f32_e32 v43, 1.0, v43
	v_sub_f32_e32 v42, v35, v42
	v_add_f32_e32 v62, v42, v43
	v_frexp_mant_f32_e32 v63, v61
	v_cvt_f64_f32_e32 v[42:43], v61
	v_cmp_gt_f32_e32 vcc, s48, v52
	v_frexp_exp_i32_f64_e32 v42, v[42:43]
	v_cmp_gt_f32_e64 s[0:1], s48, v63
	v_subbrev_co_u32_e32 v81, vcc, 0, v53, vcc
	s_nop 0
	v_subbrev_co_u32_e64 v80, s[0:1], 0, v42, s[0:1]
	v_sub_u32_e32 v42, 0, v81
	v_ldexp_f32 v43, v50, v42
	v_sub_u32_e32 v50, 0, v80
	v_ldexp_f32 v51, v51, v42
	v_ldexp_f32 v42, v61, v50
	v_pk_add_f32 v[52:53], v[42:43], 1.0 op_sel_hi:[1,0]
	v_ldexp_f32 v50, v62, v50
	v_pk_add_f32 v[62:63], v[52:53], -1.0 op_sel_hi:[1,0]
	v_pk_add_f32 v[68:69], v[42:43], -1.0 op_sel_hi:[1,0]
	v_pk_add_f32 v[62:63], v[42:43], v[62:63] neg_lo:[0,1] neg_hi:[0,1]
	v_pk_add_f32 v[70:71], v[68:69], 1.0 op_sel_hi:[1,0]
	v_pk_add_f32 v[62:63], v[50:51], v[62:63]
	v_pk_add_f32 v[42:43], v[42:43], v[70:71] neg_lo:[0,1] neg_hi:[0,1]
	v_pk_add_f32 v[64:65], v[52:53], v[62:63]
	v_pk_add_f32 v[42:43], v[50:51], v[42:43]
	v_rcp_f32_e32 v67, v65
	v_rcp_f32_e32 v66, v64
	v_pk_add_f32 v[50:51], v[68:69], v[42:43]
	v_pk_add_f32 v[52:53], v[64:65], v[52:53] neg_lo:[0,1] neg_hi:[0,1]
	v_pk_add_f32 v[68:69], v[50:51], v[68:69] neg_lo:[0,1] neg_hi:[0,1]
	v_pk_mul_f32 v[70:71], v[50:51], v[66:67]
	v_pk_add_f32 v[52:53], v[62:63], v[52:53] neg_lo:[0,1] neg_hi:[0,1]
	v_pk_mul_f32 v[62:63], v[64:65], v[70:71]
	v_pk_add_f32 v[42:43], v[42:43], v[68:69] neg_lo:[0,1] neg_hi:[0,1]
	v_pk_fma_f32 v[68:69], v[70:71], v[64:65], v[62:63] neg_lo:[0,0,1] neg_hi:[0,0,1]
	s_mov_b32 s0, 0x3e9b6dac
	v_pk_fma_f32 v[68:69], v[70:71], v[52:53], v[68:69]
	v_max_f32_e32 v40, 0, v40
	v_pk_add_f32 v[72:73], v[62:63], v[68:69]
	v_lshlrev_b32_e32 v194, 4, v32
	v_pk_add_f32 v[74:75], v[50:51], v[72:73] neg_lo:[0,1] neg_hi:[0,1]
	v_pk_add_f32 v[62:63], v[72:73], v[62:63] neg_lo:[0,1] neg_hi:[0,1]
	v_pk_add_f32 v[50:51], v[50:51], v[74:75] neg_lo:[0,1] neg_hi:[0,1]
	s_mov_b32 s13, 0
	v_pk_add_f32 v[50:51], v[50:51], v[72:73] neg_lo:[0,1] neg_hi:[0,1]
	s_nop 0
	v_pk_add_f32 v[42:43], v[42:43], v[50:51]
	v_pk_add_f32 v[50:51], v[62:63], v[68:69] neg_lo:[0,1] neg_hi:[0,1]
	s_nop 0
	v_pk_add_f32 v[42:43], v[50:51], v[42:43]
	s_nop 0
	v_pk_add_f32 v[50:51], v[74:75], v[42:43]
	s_nop 0
	v_pk_mul_f32 v[62:63], v[66:67], v[50:51]
	v_mov_b32_e32 v73, v51
	v_pk_mul_f32 v[68:69], v[64:65], v[62:63]
	v_pk_add_f32 v[74:75], v[74:75], v[50:51] neg_lo:[0,1] neg_hi:[0,1]
	v_pk_fma_f32 v[64:65], v[62:63], v[64:65], v[68:69] neg_lo:[0,0,1] neg_hi:[0,0,1]
	v_mov_b32_e32 v78, v69
	v_pk_fma_f32 v[52:53], v[62:63], v[52:53], v[64:65]
	v_pk_add_f32 v[42:43], v[42:43], v[74:75]
	v_pk_add_f32 v[64:65], v[68:69], v[52:53]
	s_nop 0
	v_pk_add_f32 v[76:77], v[50:51], v[64:65] neg_lo:[0,1] neg_hi:[0,1]
	v_mov_b32_e32 v72, v65
	v_mov_b32_e32 v79, v77
	v_pk_add_f32 v[72:73], v[72:73], v[78:79] neg_lo:[0,1] neg_hi:[0,1]
	v_mov_b32_e32 v78, v53
	v_mov_b32_e32 v79, v65
	v_pk_add_f32 v[50:51], v[50:51], v[76:77] neg_lo:[0,1] neg_hi:[0,1]
	v_pk_add_f32 v[72:73], v[72:73], v[78:79] neg_lo:[0,1] neg_hi:[0,1]
	v_pk_add_f32 v[50:51], v[50:51], v[64:65] neg_lo:[0,1] neg_hi:[0,1]
	v_pk_add_f32 v[68:69], v[64:65], v[68:69] neg_lo:[0,1] neg_hi:[0,1]
	v_mov_b32_e32 v51, v73
	v_pk_add_f32 v[42:43], v[42:43], v[50:51]
	v_pk_add_f32 v[50:51], v[68:69], v[52:53] neg_lo:[0,1] neg_hi:[0,1]
	v_pk_add_f32 v[78:79], v[70:71], v[62:63]
	v_mov_b32_e32 v51, v72
	v_pk_add_f32 v[42:43], v[50:51], v[42:43]
	v_pk_add_f32 v[50:51], v[78:79], v[70:71] neg_lo:[0,1] neg_hi:[0,1]
	v_pk_add_f32 v[42:43], v[76:77], v[42:43]
	v_pk_add_f32 v[50:51], v[62:63], v[50:51] neg_lo:[0,1] neg_hi:[0,1]
	v_pk_mul_f32 v[42:43], v[66:67], v[42:43]
	v_cvt_f32_i32_e32 v67, v81
	v_pk_add_f32 v[42:43], v[50:51], v[42:43]
	v_cvt_f32_i32_e32 v66, v80
	v_pk_add_f32 v[50:51], v[78:79], v[42:43]
	v_mul_u32_u24_e32 v80, 0x440, v33
	v_pk_mul_f32 v[62:63], v[50:51], v[50:51]
	v_pk_add_f32 v[52:53], v[50:51], v[78:79] neg_lo:[0,1] neg_hi:[0,1]
	v_pk_fma_f32 v[64:65], v[62:63], s[0:1], v[198:199] op_sel_hi:[1,0,0]
	s_mov_b32 s0, 0x3f2aaada
	v_pk_add_f32 v[42:43], v[42:43], v[52:53] neg_lo:[0,1] neg_hi:[0,1]
	v_ldexp_f32 v53, v51, 1
	v_pk_fma_f32 v[64:65], v[62:63], v[64:65], s[0:1] op_sel_hi:[1,1,0]
	v_ldexp_f32 v52, v50, 1
	v_pk_mul_f32 v[50:51], v[50:51], v[62:63]
	s_mov_b32 s0, 0x3f317218
	v_pk_mul_f32 v[50:51], v[50:51], v[64:65]
	v_pk_mul_f32 v[68:69], v[66:67], s[0:1] op_sel_hi:[1,0]
	v_pk_add_f32 v[62:63], v[52:53], v[50:51]
	v_ldexp_f32 v43, v43, 1
	v_pk_add_f32 v[52:53], v[62:63], v[52:53] neg_lo:[0,1] neg_hi:[0,1]
	v_pk_fma_f32 v[70:71], v[66:67], s[0:1], v[68:69] op_sel_hi:[1,0,1] neg_lo:[0,0,1] neg_hi:[0,0,1]
	s_mov_b32 s0, 0xb102e308
	v_ldexp_f32 v42, v42, 1
	v_pk_add_f32 v[50:51], v[50:51], v[52:53] neg_lo:[0,1] neg_hi:[0,1]
	v_pk_fma_f32 v[66:67], v[66:67], s[0:1], v[70:71] op_sel_hi:[1,0,1]
	v_pk_add_f32 v[42:43], v[42:43], v[50:51]
	v_pk_add_f32 v[70:71], v[68:69], v[66:67]
; __device__ __forceinline__ float bf2f(unsigned short v) { return __uint_as_float((unsigned)v << 16); }
; #define FIN(k) ((const float*)ptab(F.tab, (k)))
; __device__ __forceinline__ void lru_item(Frame& F, int l, int item) {
;     ...
;             const float z = -FIN(I_LRULAM)[ch]; sp8[n] = 8.f * (fmaxf(z, 0.f) + log1pf(__expf(-fabsf(z)))); }
;         const bf16* xcol = pj + 3 * AW + cch;
;         float h3 = 0.f, h2 = 0.f, h1 = 0.f;
;         if (t0 != 0) { h3 = bf2f(xcol[(size_t)(t0 - 3) * INW]); h2 = bf2f(xcol[(size_t)(t0 - 2) * INW]); h1 = bf2f(xcol[(size_t)(t0 - 1) * INW]); }
;         float hrun[2] = {0.f, 0.f}, Arun[2] = {1.f, 1.f};
;         unsigned short xq[16], xn[16];
; #pragma unroll
;         for (int tt = 0; tt < 16; ++tt) { xq[tt] = xcol[(size_t)(t0 + tt) * INW]; xn[tt] = xcol[(size_t)(t0 + 16 + tt) * INW]; }
	v_pk_add_f32 v[50:51], v[62:63], v[42:43]
	v_pk_add_f32 v[68:69], v[70:71], v[68:69] neg_lo:[0,1] neg_hi:[0,1]
	v_pk_add_f32 v[52:53], v[50:51], v[62:63] neg_lo:[0,1] neg_hi:[0,1]
	v_pk_add_f32 v[66:67], v[66:67], v[68:69] neg_lo:[0,1] neg_hi:[0,1]
	v_pk_add_f32 v[42:43], v[42:43], v[52:53] neg_lo:[0,1] neg_hi:[0,1]
	v_mov_b32_e32 v72, v51
	v_pk_add_f32 v[52:53], v[66:67], v[42:43]
	v_mov_b32_e32 v73, v71
	v_pk_add_f32 v[62:63], v[52:53], v[66:67] neg_lo:[0,1] neg_hi:[0,1]
	s_mov_b32 s0, 0x7f800000
	v_pk_add_f32 v[64:65], v[52:53], v[62:63] neg_lo:[0,1] neg_hi:[0,1]
	v_pk_add_f32 v[42:43], v[42:43], v[62:63] neg_lo:[0,1] neg_hi:[0,1]
	v_pk_add_f32 v[62:63], v[70:71], v[50:51]
	v_pk_add_f32 v[64:65], v[66:67], v[64:65] neg_lo:[0,1] neg_hi:[0,1]
	v_pk_add_f32 v[66:67], v[62:63], v[70:71] neg_lo:[0,1] neg_hi:[0,1]
	v_mov_b32_e32 v51, v70
	v_pk_add_f32 v[68:69], v[62:63], v[66:67] neg_lo:[0,1] neg_hi:[0,1]
	v_mov_b32_e32 v74, v67
	v_mov_b32_e32 v75, v69
	v_mov_b32_e32 v67, v68
	v_pk_add_f32 v[72:73], v[72:73], v[74:75] neg_lo:[0,1] neg_hi:[0,1]
	v_pk_add_f32 v[50:51], v[50:51], v[66:67] neg_lo:[0,1] neg_hi:[0,1]
	v_pk_add_f32 v[72:73], v[72:73], v[72:73] op_sel_hi:[0,1]
	v_pk_add_f32 v[50:51], v[50:51], v[50:51] op_sel:[0,1] op_sel_hi:[1,0]
	v_pk_add_f32 v[42:43], v[42:43], v[64:65]
	v_mov_b32_e32 v51, v53
	v_mov_b32_e32 v53, v73
	v_pk_add_f32 v[50:51], v[50:51], v[52:53]
	v_cmp_neq_f32_e32 vcc, s0, v35
	v_pk_add_f32 v[52:53], v[62:63], v[50:51]
	s_nop 0
	v_pk_add_f32 v[62:63], v[52:53], v[62:63] neg_lo:[0,1] neg_hi:[0,1]
	s_nop 0
	v_pk_add_f32 v[50:51], v[50:51], v[62:63] neg_lo:[0,1] neg_hi:[0,1]
	s_nop 0
	v_pk_add_f32 v[42:43], v[42:43], v[50:51]
	s_nop 0
	v_pk_add_f32 v[42:43], v[52:53], v[42:43]
	s_nop 0
	v_cndmask_b32_e32 v42, v245, v42, vcc
	v_cmp_neq_f32_e32 vcc, s0, v39
	s_mov_b32 s0, 0x33800000
	s_nop 0
	v_cndmask_b32_e32 v43, v245, v43, vcc
	v_cmp_ngt_f32_e32 vcc, -1.0, v39
	s_nop 1
	v_cndmask_b32_e32 v43, v246, v43, vcc
	v_cmp_ngt_f32_e32 vcc, -1.0, v35
	s_nop 1
	v_cndmask_b32_e32 v42, v246, v42, vcc
	v_cmp_neq_f32_e32 vcc, -1.0, v35
	s_nop 1
	v_cndmask_b32_e32 v42, v243, v42, vcc
	v_cmp_neq_f32_e32 vcc, -1.0, v39
	s_nop 1
	v_cndmask_b32_e32 v43, v243, v43, vcc
	v_cmp_lt_f32_e64 vcc, |v35|, s0
	v_cmp_lt_f32_e64 s[0:1], |v39|, s0
	s_nop 0
	v_cndmask_b32_e32 v42, v42, v35, vcc
	v_cndmask_b32_e64 v43, v43, v39, s[0:1]
	v_pk_add_f32 v[40:41], v[40:41], v[42:43]
	v_mad_i64_i32 v[42:43], s[28:29], s23, v244, v[36:37]
	s_or_b32 s1, s23, 16
	global_load_ushort v95, v[42:43], off offset:3072
	v_mad_i64_i32 v[42:43], s[28:29], s1, v244, v[36:37]
	s_or_b32 s1, s23, 1
	global_load_ushort v61, v[42:43], off offset:3072
	v_mad_i64_i32 v[42:43], s[28:29], s1, v244, v[36:37]
	s_or_b32 s1, s23, 17
	global_load_ushort v94, v[42:43], off offset:3072
	v_mad_i64_i32 v[42:43], s[28:29], s1, v244, v[36:37]
	s_or_b32 s1, s23, 2
	global_load_ushort v62, v[42:43], off offset:3072
	v_mad_i64_i32 v[42:43], s[28:29], s1, v244, v[36:37]
	s_or_b32 s1, s23, 18
	global_load_ushort v93, v[42:43], off offset:3072
	v_mad_i64_i32 v[42:43], s[28:29], s1, v244, v[36:37]
	s_or_b32 s1, s23, 3
	global_load_ushort v63, v[42:43], off offset:3072
	v_mad_i64_i32 v[42:43], s[28:29], s1, v244, v[36:37]
	s_or_b32 s1, s23, 19
	global_load_ushort v91, v[42:43], off offset:3072
	v_mad_i64_i32 v[42:43], s[28:29], s1, v244, v[36:37]
	s_or_b32 s1, s23, 4
	global_load_ushort v64, v[42:43], off offset:3072
	v_mad_i64_i32 v[42:43], s[28:29], s1, v244, v[36:37]
	s_or_b32 s1, s23, 20
	global_load_ushort v92, v[42:43], off offset:3072
	v_mad_i64_i32 v[42:43], s[28:29], s1, v244, v[36:37]
	s_or_b32 s1, s23, 5
	global_load_ushort v65, v[42:43], off offset:3072
	v_mad_i64_i32 v[42:43], s[28:29], s1, v244, v[36:37]
	s_or_b32 s1, s23, 21
	global_load_ushort v90, v[42:43], off offset:3072
	v_mad_i64_i32 v[42:43], s[28:29], s1, v244, v[36:37]
	s_or_b32 s1, s23, 6
	global_load_ushort v66, v[42:43], off offset:3072
	v_mad_i64_i32 v[42:43], s[28:29], s1, v244, v[36:37]
	s_or_b32 s1, s23, 22
	global_load_ushort v89, v[42:43], off offset:3072
	v_mad_i64_i32 v[42:43], s[28:29], s1, v244, v[36:37]
	s_or_b32 s1, s23, 7
	global_load_ushort v67, v[42:43], off offset:3072
	v_mad_i64_i32 v[42:43], s[28:29], s1, v244, v[36:37]
	s_or_b32 s1, s23, 23
	global_load_ushort v87, v[42:43], off offset:3072
	v_mad_i64_i32 v[42:43], s[28:29], s1, v244, v[36:37]
	s_or_b32 s1, s23, 8
	global_load_ushort v68, v[42:43], off offset:3072
	v_mad_i64_i32 v[42:43], s[28:29], s1, v244, v[36:37]
	s_or_b32 s1, s23, 24
	global_load_ushort v88, v[42:43], off offset:3072
	v_mad_i64_i32 v[42:43], s[28:29], s1, v244, v[36:37]
	s_or_b32 s1, s23, 9
	global_load_ushort v69, v[42:43], off offset:3072
	v_mad_i64_i32 v[42:43], s[28:29], s1, v244, v[36:37]
	s_or_b32 s1, s23, 25
	global_load_ushort v86, v[42:43], off offset:3072
	v_mad_i64_i32 v[42:43], s[28:29], s1, v244, v[36:37]
	s_or_b32 s1, s23, 10
	global_load_ushort v70, v[42:43], off offset:3072
	v_mad_i64_i32 v[42:43], s[28:29], s1, v244, v[36:37]
	s_or_b32 s1, s23, 26
	global_load_ushort v111, v[42:43], off offset:3072
	v_mad_i64_i32 v[42:43], s[28:29], s1, v244, v[36:37]
	s_or_b32 s1, s23, 11
	global_load_ushort v71, v[42:43], off offset:3072
	v_mad_i64_i32 v[42:43], s[28:29], s1, v244, v[36:37]
	s_or_b32 s1, s23, 27
	global_load_ushort v109, v[42:43], off offset:3072
	v_mad_i64_i32 v[42:43], s[28:29], s1, v244, v[36:37]
	s_or_b32 s1, s23, 12
	global_load_ushort v72, v[42:43], off offset:3072
	v_mad_i64_i32 v[42:43], s[28:29], s1, v244, v[36:37]
	s_or_b32 s1, s23, 28
	global_load_ushort v110, v[42:43], off offset:3072
	v_mad_i64_i32 v[42:43], s[28:29], s1, v244, v[36:37]
; __device__ __forceinline__ float bf2f(unsigned short v) { return __uint_as_float((unsigned)v << 16); }
; __device__ __forceinline__ void lru_item(Frame& F, int l, int item) {
;     ...
;         const bf16* xcol = pj + 3 * AW + cch;
;         float h3 = 0.f, h2 = 0.f, h1 = 0.f;
;         if (t0 != 0) { h3 = bf2f(xcol[(size_t)(t0 - 3) * INW]); h2 = bf2f(xcol[(size_t)(t0 - 2) * INW]); h1 = bf2f(xcol[(size_t)(t0 - 1) * INW]); }
;         float hrun[2] = {0.f, 0.f}, Arun[2] = {1.f, 1.f};
;         unsigned short xq[16], xn[16];
; #pragma unroll
;         for (int tt = 0; tt < 16; ++tt) { xq[tt] = xcol[(size_t)(t0 + tt) * INW]; xn[tt] = xcol[(size_t)(t0 + 16 + tt) * INW]; }
; #pragma unroll 1
;         for (int sc = 0; sc < 16; ++sc) {
;             const int ts = t0 + sc * 16, tn = (sc < 14) ? ts + 32 : ts;
;             unsigned short xnn[16];
; #pragma unroll
;             for (int tt = 0; tt < 16; ++tt) xnn[tt] = xcol[(size_t)(tn + tt) * INW];
; #pragma unroll
;             for (int tt = 0; tt < 16; ++tt) { const float xv = bf2f(xq[tt]); const float xc = cb + cw0 * h3 + cw1 * h2 + cw2 * h1 + cw3 * xv; h3 = h2; h2 = h1; h1 = xv; xcs[tt * 68 + lane] = xc; }
	s_or_b32 s1, s23, 13
	global_load_ushort v73, v[42:43], off offset:3072
	v_mad_i64_i32 v[42:43], s[28:29], s1, v244, v[36:37]
	s_or_b32 s1, s23, 29
	global_load_ushort v108, v[42:43], off offset:3072
	v_mad_i64_i32 v[42:43], s[28:29], s1, v244, v[36:37]
	s_or_b32 s1, s23, 14
	global_load_ushort v74, v[42:43], off offset:3072
	v_mad_i64_i32 v[42:43], s[28:29], s1, v244, v[36:37]
	s_or_b32 s1, s23, 30
	global_load_ushort v106, v[42:43], off offset:3072
	v_mad_i64_i32 v[42:43], s[28:29], s1, v244, v[36:37]
	s_or_b32 s1, s23, 15
	global_load_ushort v75, v[42:43], off offset:3072
	v_mad_i64_i32 v[42:43], s[28:29], s1, v244, v[36:37]
	s_or_b32 s1, s23, 31
	global_load_ushort v107, v[42:43], off offset:3072
	v_mad_i64_i32 v[42:43], s[28:29], s1, v244, v[36:37]
	global_load_ushort v76, v[42:43], off offset:3072
	s_mul_i32 s0, s12, 0x1100
	s_add_i32 s0, s0, 0
	v_mov_b32_e32 v35, s0
	v_lshl_add_u32 v77, v32, 2, s0
	s_add_i32 s0, s0, s16
	s_movk_i32 s1, 0x110
	v_lshl_add_u32 v79, v44, 2, s0
	s_add_u32 s0, s21, s14
	v_mad_u32_u24 v35, v44, s1, v35
	s_addc_u32 s1, s22, s15
	v_or_b32_e32 v42, v44, v206
	s_add_u32 s0, s27, s0
	v_lshlrev_b32_e32 v39, 5, v33
	v_lshlrev_b32_e32 v50, 2, v42
	s_addc_u32 s1, s26, s1
	v_pk_mul_f32 v[40:41], v[40:41], s[92:93] op_sel_hi:[1,0]
	v_or_b32_e32 v51, 64, v50
	v_or_b32_e32 v52, 0x80, v50
	v_or_b32_e32 v53, 0xc0, v50
	v_lshl_add_u64 v[42:43], s[0:1], 0, v[194:195]
	v_add_u32_e32 v78, v35, v39
	v_add_u32_e32 v79, v79, v80
	s_mov_b32 s16, s23
	v_mov_b32_e32 v35, v34
	v_mov_b32_e32 v39, v38
	v_subrev_u32_e32 v124, s8, v36
	v_add_u32_e32 v125, 0x1400, v124
	v_add_u32_e32 v126, 0x2800, v124
	v_add_u32_e32 v127, 0x3c00, v124
	v_add_u32_e32 v128, 0x5000, v124
	v_add_u32_e32 v129, 0x6400, v124
	v_add_u32_e32 v130, 0x7800, v124
	v_add_u32_e32 v131, 0x8c00, v124
	v_add_u32_e32 v132, 0xa000, v124
	v_add_u32_e32 v133, 0xb400, v124
	v_add_u32_e32 v134, 0xc800, v124
	v_add_u32_e32 v135, 0xdc00, v124
	v_add_u32_e32 v136, 0xf000, v124
	v_add_u32_e32 v137, 0x10400, v124
	v_add_u32_e32 v138, 0x11800, v124
	v_add_u32_e32 v139, 0x12c00, v124
.LBB0_467:
	v_fma_f32 v58, v45, v58, v49
	v_fmac_f32_e32 v58, v46, v60
	v_fma_f32 v60, v45, v60, v49
	s_add_i32 s0, s16, 32
	s_waitcnt vmcnt(31)
	v_lshlrev_b32_e32 v95, 16, v95
	v_fmac_f32_e32 v60, v46, v59
	s_cmp_lt_u32 s13, 14
	v_fmac_f32_e32 v58, v47, v59
	s_waitcnt vmcnt(29)
	v_lshlrev_b32_e32 v94, 16, v94
	v_fmac_f32_e32 v60, v47, v95
	s_cselect_b32 s17, s0, s16
	s_mul_i32 s98, s17, 0x1400
	s_add_u32 s98, s8, s98
	s_addc_u32 s99, s9, 0
	v_fmac_f32_e32 v58, v48, v95
	v_fmac_f32_e32 v60, v48, v94
	s_waitcnt vmcnt(16)
	v_mov_b32_e32 v104, v62
	s_waitcnt vmcnt(15)
	v_mov_b32_e32 v103, v63
	ds_write2_b32 v77, v58, v60 offset1:68
	v_fma_f32 v59, v45, v59, v49
	s_waitcnt vmcnt(25)
	v_lshlrev_b32_e32 v60, 16, v91
	v_fma_f32 v91, v45, v95, v49
	v_lshlrev_b32_e32 v58, 16, v93
	v_fmac_f32_e32 v59, v46, v95
	v_fmac_f32_e32 v91, v46, v94
	v_mov_b32_e32 v105, v61
	global_load_ushort v61, v124, s[98:99] offset:3072
	v_fmac_f32_e32 v59, v47, v94
	v_fmac_f32_e32 v91, v47, v58
	v_fmac_f32_e32 v59, v48, v58
	v_fmac_f32_e32 v91, v48, v60
	s_waitcnt vmcnt(15)
	v_mov_b32_e32 v102, v64
	s_waitcnt vmcnt(14)
	v_mov_b32_e32 v101, v65
	ds_write2_b32 v77, v59, v91 offset0:136 offset1:204
	v_fma_f32 v91, v45, v94, v49
	v_fmac_f32_e32 v91, v46, v58
	v_fma_f32 v58, v45, v58, v49
	global_load_ushort v62, v125, s[98:99] offset:3072
	v_lshlrev_b32_e32 v59, 16, v92
	global_load_ushort v63, v126, s[98:99] offset:3072
	v_fmac_f32_e32 v58, v46, v60
	v_fmac_f32_e32 v91, v47, v60
	s_waitcnt vmcnt(24)
	v_lshlrev_b32_e32 v90, 16, v90
	v_fmac_f32_e32 v58, v47, v59
	v_fma_f32 v60, v45, v60, v49
	s_waitcnt vmcnt(15)
	v_mov_b32_e32 v100, v66
	s_waitcnt vmcnt(14)
	v_mov_b32_e32 v99, v67
	v_fmac_f32_e32 v91, v48, v59
	v_fmac_f32_e32 v58, v48, v90
	v_add_u32_e32 v92, 0x400, v77
	v_fmac_f32_e32 v60, v46, v59
	v_fma_f32 v59, v45, v59, v49
	ds_write2_b32 v92, v91, v58 offset0:16 offset1:84
	v_lshlrev_b32_e32 v58, 16, v89
	v_fmac_f32_e32 v59, v46, v90
	global_load_ushort v64, v127, s[98:99] offset:3072
	v_fmac_f32_e32 v60, v47, v90
	global_load_ushort v65, v128, s[98:99] offset:3072
	s_waitcnt vmcnt(22)
	v_lshlrev_b32_e32 v87, 16, v87
	v_fmac_f32_e32 v59, v47, v58
	v_fmac_f32_e32 v60, v48, v58
	v_fmac_f32_e32 v59, v48, v87
	s_waitcnt vmcnt(15)
	v_mov_b32_e32 v98, v68
	s_waitcnt vmcnt(14)
	v_mov_b32_e32 v97, v69
	ds_write2_b32 v92, v60, v59 offset0:152 offset1:220
	v_fma_f32 v60, v45, v90, v49
	v_fmac_f32_e32 v60, v46, v58
	v_fma_f32 v58, v45, v58, v49
	global_load_ushort v66, v129, s[98:99] offset:3072
	v_lshlrev_b32_e32 v59, 16, v88
	global_load_ushort v67, v130, s[98:99] offset:3072
	v_fmac_f32_e32 v58, v46, v87
	v_fmac_f32_e32 v60, v47, v87
	s_waitcnt vmcnt(20)
	v_lshlrev_b32_e32 v86, 16, v86
	v_fmac_f32_e32 v58, v47, v59
	s_waitcnt vmcnt(15)
	v_mov_b32_e32 v96, v70
	s_waitcnt vmcnt(14)
	v_mov_b32_e32 v85, v71
	v_fmac_f32_e32 v60, v48, v59
	v_fmac_f32_e32 v58, v48, v86
	v_add_u32_e32 v88, 0x800, v77
	ds_write2_b32 v88, v60, v58 offset0:32 offset1:100
	v_fma_f32 v58, v45, v87, v49
	global_load_ushort v68, v131, s[98:99] offset:3072
	v_fmac_f32_e32 v58, v46, v59
	global_load_ushort v69, v132, s[98:99] offset:3072
	v_fma_f32 v59, v45, v59, v49
	v_lshlrev_b32_e32 v60, 16, v111
	v_fmac_f32_e32 v59, v46, v86
	s_waitcnt vmcnt(14)
	v_mov_b32_e32 v83, v73
	v_mov_b32_e32 v84, v72
	v_fmac_f32_e32 v58, v47, v86
	v_lshlrev_b32_e32 v87, 16, v109
	v_fmac_f32_e32 v59, v47, v60
	v_fmac_f32_e32 v58, v48, v60
	v_fmac_f32_e32 v59, v48, v87
	global_load_ushort v70, v133, s[98:99] offset:3072
	ds_write2_b32 v88, v58, v59 offset0:168 offset1:236
	global_load_ushort v71, v134, s[98:99] offset:3072
	v_fma_f32 v59, v45, v86, v49
	v_fmac_f32_e32 v59, v46, v60
	v_fma_f32 v60, v45, v60, v49
	s_waitcnt vmcnt(13)
; #define LAS __attribute__((address_space(3)))
; __device__ __forceinline__ void lru_item(Frame& F, int l, int item) {
;     ...
;             for (int tt = 0; tt < 16; ++tt) xnn[tt] = xcol[(size_t)(tn + tt) * INW];
; #pragma unroll
;             for (int tt = 0; tt < 16; ++tt) { const float xv = bf2f(xq[tt]); const float xc = cb + cw0 * h3 + cw1 * h2 + cw2 * h1 + cw3 * xv; h3 = h2; h2 = h1; h1 = xv; xcs[tt * 68 + lane] = xc; }
;             asm volatile("s_waitcnt lgkmcnt(0)" ::: "memory");
;             bf16x8 Af[2];
; #pragma unroll
;             for (int kk = 0; kk < 2; ++kk) { const LAS f32x4* ap = (const LAS f32x4*)(xcs + r * 68 + 32 * kk + 8 * q); const f32x4 a0 = ap[0], a1 = ap[1];
;                 v4u pw; pw.x = pk2(a0.x, a0.y); pw.y = pk2(a0.z, a0.w); pw.z = pk2(a1.x, a1.y); pw.w = pk2(a1.z, a1.w); Af[kk] = __builtin_bit_cast(bf16x8, pw); }
;             f32x4 Da[2], Dx[2];
; #pragma unroll
;             for (int n = 0; n < 2; ++n) { Da[n] = (f32x4){0.f, 0.f, 0.f, 0.f}; Dx[n] = Da[n];
; #pragma unroll
;                 for (int kk = 0; kk < 2; ++kk) { Da[n] = __builtin_amdgcn_mfma_f32_16x16x32_bf16(Af[kk], Bf[0][n][kk], Da[n], 0, 0, 0); Dx[n] = __builtin_amdgcn_mfma_f32_16x16x32_bf16(Af[kk], Bf[1][n][kk], Dx[n], 0, 0, 0); } }
; #pragma unroll
;             for (int n = 0; n < 2; ++n) {
;                 float a[4], bb[4]; v4u st;
; #pragma unroll
;                 for (int i = 0; i < 4; ++i) { const float xcv = xcs[(4 * q + i) * 68 + hf * 32 + 16 * n + r];
;                     const float ra = sigmoid_f(Da[n][i] + ba[n]), ix = sigmoid_f(Dx[n][i] + bx[n]);
;                     const float la = -ra * sp8[n];
;                     const float y2 = 2.f * la;
;                     const float ser = -y2 * (1.f + y2 * (0.5f + y2 * (0.16666667f + y2 * (0.041666668f + y2 * 0.008333334f))));
;                     const float av = __builtin_amdgcn_exp2f(1.4426950408889634f * la);
;                     const float em = (y2 > -0.25f) ? ser : (1.f - av * av);
;                     const float bv = __builtin_amdgcn_sqrtf(fmaxf(em, 0.f)) * (ix * xcv);
;                     const unsigned pr = pk2(la * 1.4426950408889634f, bv); st[i] = pr;
;                     a[i] = __builtin_amdgcn_exp2f(bf2f((unsigned short)(pr & 0xffffu))); bb[i] = __uint_as_float(pr & 0xffff0000u); }
	v_mov_b32_e32 v81, v75
	v_mov_b32_e32 v82, v74
	v_lshlrev_b32_e32 v88, 16, v110
	v_fmac_f32_e32 v60, v46, v87
	v_fmac_f32_e32 v59, v47, v87
	v_lshlrev_b32_e32 v58, 16, v108
	v_fmac_f32_e32 v60, v47, v88
	v_fma_f32 v87, v45, v87, v49
	global_load_ushort v72, v135, s[98:99] offset:3072
	v_fmac_f32_e32 v59, v48, v88
	global_load_ushort v73, v136, s[98:99] offset:3072
	v_fmac_f32_e32 v60, v48, v58
	v_add_u32_e32 v86, 0xc00, v77
	v_fmac_f32_e32 v87, v46, v88
	v_fma_f32 v88, v45, v88, v49
	ds_write2_b32 v86, v59, v60 offset0:48 offset1:116
	v_lshlrev_b32_e32 v60, 16, v106
	v_fmac_f32_e32 v88, v46, v58
	v_fmac_f32_e32 v87, v47, v58
	s_waitcnt vmcnt(14)
	v_lshlrev_b32_e32 v59, 16, v107
	v_fmac_f32_e32 v88, v47, v60
	v_fmac_f32_e32 v87, v48, v60
	v_fmac_f32_e32 v88, v48, v59
	global_load_ushort v74, v137, s[98:99] offset:3072
	ds_write2_b32 v86, v87, v88 offset0:184 offset1:252
	global_load_ushort v75, v138, s[98:99] offset:3072
	s_waitcnt vmcnt(15)
	v_mov_b32_e32 v80, v76
	global_load_ushort v76, v139, s[98:99] offset:3072
	s_waitcnt lgkmcnt(0)
	ds_read_b128 v[86:89], v78
	ds_read_b128 v[90:93], v78 offset:16
	s_waitcnt lgkmcnt(1)
	v_cvt_pk_bf16_f32 v86, v86, v87
	v_cvt_pk_bf16_f32 v87, v88, v89
	s_waitcnt lgkmcnt(0)
	v_cvt_pk_bf16_f32 v88, v90, v91
	v_cvt_pk_bf16_f32 v89, v92, v93
	ds_read_b128 v[90:93], v78 offset:128
	ds_read_b128 v[106:109], v78 offset:144
	s_waitcnt lgkmcnt(1)
	v_cvt_pk_bf16_f32 v90, v90, v91
	v_cvt_pk_bf16_f32 v91, v92, v93
	s_waitcnt lgkmcnt(0)
	v_cvt_pk_bf16_f32 v92, v106, v107
	v_cvt_pk_bf16_f32 v93, v108, v109
	v_mfma_f32_16x16x32_bf16 v[106:109], v[86:89], v[0:3], 0
	ds_read2_b32 v[94:95], v79 offset1:16
	ds_read2_b32 v[118:119], v79 offset0:68 offset1:84
	ds_read2_b32 v[120:121], v79 offset0:136 offset1:152
	v_mfma_f32_16x16x32_bf16 v[110:113], v[86:89], v[16:19], 0
	ds_read2_b32 v[122:123], v79 offset0:204 offset1:220
	s_add_i32 s13, s13, 1
	s_add_i32 s16, s16, 16
	v_mfma_f32_16x16x32_bf16 v[106:109], v[90:93], v[4:7], v[106:109]
	s_cmp_eq_u32 s13, 16
	v_mfma_f32_16x16x32_bf16 v[114:117], v[86:89], v[8:11], 0
	v_mfma_f32_16x16x32_bf16 v[86:89], v[86:89], v[24:27], 0
	v_mfma_f32_16x16x32_bf16 v[110:113], v[90:93], v[20:23], v[110:113]
	v_mfma_f32_16x16x32_bf16 v[114:117], v[90:93], v[12:15], v[114:117]
	v_mfma_f32_16x16x32_bf16 v[86:89], v[90:93], v[28:31], v[86:89]
	s_nop 1
	v_add_f32_e32 v90, v54, v106
	v_mul_f32_e32 v90, 0xbfb8aa3b, v90
	v_exp_f32_e32 v90, v90
	s_nop 0
	v_add_f32_e32 v91, v55, v110
	v_mul_f32_e32 v91, 0xbfb8aa3b, v91
	v_exp_f32_e32 v91, v91
	v_add_f32_e32 v90, 1.0, v90
	v_rcp_f32_e64 v90, -v90
	v_add_f32_e32 v86, v57, v86
	v_add_f32_e32 v91, 1.0, v91
	v_rcp_f32_e32 v91, v91
	v_mul_f32_e32 v90, v41, v90
	v_add_f32_e32 v92, v90, v90
	v_mul_f32_e32 v90, 0x3fb8aa3b, v90
	v_fmamk_f32 v93, v92, 0x3c088889, v239
	v_exp_f32_e32 v106, v90
	v_fmaak_f32 v93, v92, v93, 0x3e2aaaab
	v_fma_f32 v93, v92, v93, 0.5
	v_fma_f32 v93, v92, v93, 1.0
	v_mul_f32_e64 v93, v93, -v92
	v_cmp_lt_f32_e32 vcc, s80, v92
	v_fma_f32 v92, -v106, v106, 1.0
	s_waitcnt lgkmcnt(3)
	v_mul_f32_e32 v91, v94, v91
	v_cndmask_b32_e32 v92, v92, v93, vcc
	v_max_f32_e32 v92, 0, v92
	v_sqrt_f32_e32 v92, v92
	v_mul_f32_e32 v86, 0xbfb8aa3b, v86
	v_exp_f32_e32 v86, v86
	v_add_f32_e32 v87, v57, v87
	v_mul_f32_e32 v91, v91, v92
	v_cvt_pk_bf16_f32 v90, v90, v91
	v_add_f32_e32 v92, v55, v111
	v_lshlrev_b32_e32 v91, 16, v90
	v_exp_f32_e32 v106, v91
	v_add_f32_e32 v91, v54, v107
	v_mul_f32_e32 v91, 0xbfb8aa3b, v91
	v_exp_f32_e32 v91, v91
	v_mul_f32_e32 v92, 0xbfb8aa3b, v92
	v_exp_f32_e32 v92, v92
	v_and_b32_e32 v93, 0xffff0000, v90
	v_add_f32_e32 v91, 1.0, v91
	v_rcp_f32_e64 v91, -v91
	v_add_f32_e32 v92, 1.0, v92
	v_rcp_f32_e32 v92, v92
	v_add_f32_e32 v86, 1.0, v86
	v_mul_f32_e32 v91, v41, v91
	v_add_f32_e32 v94, v91, v91
	v_mul_f32_e32 v91, 0x3fb8aa3b, v91
	v_fmamk_f32 v107, v94, 0x3c088889, v239
	v_exp_f32_e32 v110, v91
	v_fmaak_f32 v107, v94, v107, 0x3e2aaaab
	v_fma_f32 v107, v94, v107, 0.5
	v_fma_f32 v107, v94, v107, 1.0
	v_mul_f32_e64 v107, v107, -v94
	v_cmp_lt_f32_e32 vcc, s80, v94
	v_fma_f32 v94, -v110, v110, 1.0
	s_waitcnt lgkmcnt(2)
	v_mul_f32_e32 v92, v92, v118
	v_cndmask_b32_e32 v94, v94, v107, vcc
	v_max_f32_e32 v94, 0, v94
	v_sqrt_f32_e32 v94, v94
	v_add_f32_e32 v107, v55, v112
	v_mul_f32_e32 v107, 0xbfb8aa3b, v107
	v_exp_f32_e32 v107, v107
	v_mul_f32_e32 v92, v92, v94
	v_cvt_pk_bf16_f32 v91, v91, v92
	v_rcp_f32_e32 v86, v86
	v_lshlrev_b32_e32 v92, 16, v91
	v_exp_f32_e32 v110, v92
	v_add_f32_e32 v92, v54, v108
	v_mul_f32_e32 v92, 0xbfb8aa3b, v92
	v_exp_f32_e32 v92, v92
	v_add_f32_e32 v107, 1.0, v107
	v_rcp_f32_e32 v107, v107
	v_and_b32_e32 v94, 0xffff0000, v91
	v_add_f32_e32 v92, 1.0, v92
	v_rcp_f32_e64 v92, -v92
	s_waitcnt lgkmcnt(1)
	v_mul_f32_e32 v107, v107, v120
	v_fmac_f32_e32 v94, v110, v93
	v_add_f32_e32 v93, v56, v114
	v_mul_f32_e32 v92, v41, v92
	v_add_f32_e32 v108, v92, v92
	v_mul_f32_e32 v92, 0x3fb8aa3b, v92
	v_fmamk_f32 v111, v108, 0x3c088889, v239
	v_exp_f32_e32 v112, v92
	v_fmaak_f32 v111, v108, v111, 0x3e2aaaab
	v_fma_f32 v111, v108, v111, 0.5
	v_fma_f32 v111, v108, v111, 1.0
	v_mul_f32_e64 v111, v111, -v108
	v_cmp_lt_f32_e32 vcc, s80, v108
	v_fma_f32 v108, -v112, v112, 1.0
	v_mul_f32_e32 v93, 0xbfb8aa3b, v93
	v_cndmask_b32_e32 v108, v108, v111, vcc
	v_max_f32_e32 v108, 0, v108
	v_sqrt_f32_e32 v108, v108
	v_exp_f32_e32 v93, v93
	v_mul_f32_e32 v86, v86, v95
	v_mul_f32_e32 v87, 0xbfb8aa3b, v87
	v_mul_f32_e32 v107, v107, v108
	v_add_f32_e32 v108, v54, v109
	v_mul_f32_e32 v108, 0xbfb8aa3b, v108
	v_exp_f32_e32 v108, v108
	v_add_f32_e32 v93, 1.0, v93
	v_cvt_pk_bf16_f32 v92, v92, v107
	v_exp_f32_e32 v87, v87
	v_add_f32_e32 v108, 1.0, v108
	v_rcp_f32_e32 v109, v108
	v_add_f32_e32 v108, v55, v113
	v_mul_f32_e32 v108, 0xbfb8aa3b, v108
	v_exp_f32_e32 v108, v108
	v_lshlrev_b32_e32 v107, 16, v92
	v_exp_f32_e32 v107, v107
	v_and_b32_e32 v118, 0xffff0000, v92
	v_add_f32_e32 v108, 1.0, v108
	v_rcp_f32_e32 v108, v108
	v_fmac_f32_e32 v118, v107, v94
	v_add_f32_e32 v87, 1.0, v87
	v_rcp_f32_e32 v87, v87
	s_waitcnt lgkmcnt(0)
; __device__ __forceinline__ unsigned pk2(float lo, float hi) { unsigned r; asm("v_cvt_pk_bf16_f32 %0, %1, %2" : "=v"(r) : "v"(lo), "v"(hi)); return r; }
; __device__ __forceinline__ float bf2f(unsigned short v) { return __uint_as_float((unsigned)v << 16); }
; __device__ __forceinline__ void lru_item(Frame& F, int l, int item) {
;     ...
;             for (int n = 0; n < 2; ++n) {
;                 float a[4], bb[4]; v4u st;
; #pragma unroll
;                 for (int i = 0; i < 4; ++i) { const float xcv = xcs[(4 * q + i) * 68 + hf * 32 + 16 * n + r];
;                     const float ra = sigmoid_f(Da[n][i] + ba[n]), ix = sigmoid_f(Dx[n][i] + bx[n]);
;                     const float la = -ra * sp8[n];
;                     const float y2 = 2.f * la;
;                     const float ser = -y2 * (1.f + y2 * (0.5f + y2 * (0.16666667f + y2 * (0.041666668f + y2 * 0.008333334f))));
;                     const float av = __builtin_amdgcn_exp2f(1.4426950408889634f * la);
;                     const float em = (y2 > -0.25f) ? ser : (1.f - av * av);
;                     const float bv = __builtin_amdgcn_sqrtf(fmaxf(em, 0.f)) * (ix * xcv);
;                     const unsigned pr = pk2(la * 1.4426950408889634f, bv); st[i] = pr;
;                     a[i] = __builtin_amdgcn_exp2f(bf2f((unsigned short)(pr & 0xffffu))); bb[i] = __uint_as_float(pr & 0xffff0000u); }
;                 lb[(sc * 2 + n) * 64] = st;
;                 const float Al = (a[0] * a[1]) * (a[2] * a[3]);
;                 const float Hl = ((bb[0] * a[1] + bb[1]) * a[2] + bb[2]) * a[3] + bb[3];
;                 const float A0 = __shfl(Al, r), A1 = __shfl(Al, r + 16), A2 = __shfl(Al, r + 32), A3 = __shfl(Al, r + 48);
;                 const float H0 = __shfl(Hl, r), H1 = __shfl(Hl, r + 16), H2 = __shfl(Hl, r + 32), H3 = __shfl(Hl, r + 48);
;                 const float c0 = hrun[n], c1 = A0 * c0 + H0, c2 = A1 * c1 + H1, c3 = A2 * c2 + H2, c4 = A3 * c3 + H3;
;                 hrun[n] = c4; Arun[n] *= (A0 * A1) * (A2 * A3);
;             }
; #pragma unroll
;             for (int tt = 0; tt < 16; ++tt) { xq[tt] = xn[tt]; xn[tt] = xnn[tt]; }
;         }
;         if (q == 0) {
; #pragma unroll
;             for (int n = 0; n < 2; ++n) { car[w * 64 + n * 16 + r] = Arun[n]; car[w * 64 + 32 + n * 16 + r] = hrun[n]; } }
	v_mul_f32_e32 v111, v108, v122
	v_rcp_f32_e32 v108, v93
	v_add_f32_e32 v88, v57, v88
	v_mul_f32_e32 v87, v87, v119
	v_mul_f32_e32 v88, 0xbfb8aa3b, v88
	v_pk_mul_f32 v[108:109], v[40:41], v[108:109] neg_lo:[0,1] neg_hi:[0,1]
	v_exp_f32_e32 v88, v88
	v_pk_add_f32 v[112:113], v[108:109], v[108:109]
	v_mul_f32_e32 v94, 0x3fb8aa3b, v109
	v_fmamk_f32 v93, v113, 0x3c088889, v239
	v_exp_f32_e32 v109, v94
	v_fmaak_f32 v93, v113, v93, 0x3e2aaaab
	v_fma_f32 v93, v113, v93, 0.5
	v_fma_f32 v93, v113, v93, 1.0
	v_mul_f32_e64 v93, v93, -v113
	v_fma_f32 v109, -v109, v109, 1.0
	v_cmp_lt_f32_e64 s[0:1], s80, v113
	v_cmp_lt_f32_e32 vcc, s80, v112
	v_add_f32_e32 v88, 1.0, v88
	v_cndmask_b32_e64 v93, v109, v93, s[0:1]
	v_max_f32_e32 v93, 0, v93
	v_sqrt_f32_e32 v93, v93
	v_rcp_f32_e32 v88, v88
	v_add_f32_e32 v89, v57, v89
	v_mul_f32_e32 v89, 0xbfb8aa3b, v89
	v_mul_f32_e32 v93, v111, v93
	v_cvt_pk_bf16_f32 v93, v94, v93
	global_store_dwordx4 v[42:43], v[90:93], off
	v_lshlrev_b32_e32 v94, 16, v93
	v_exp_f32_e32 v111, v94
	v_and_b32_e32 v109, 0xffff0000, v93
	v_mul_f32_e32 v93, 0x3fb8aa3b, v108
	v_mul_f32_e32 v88, v88, v121
	v_pk_mul_f32 v[90:91], v[106:107], v[110:111]
	v_exp_f32_e32 v107, v93
	v_pk_mul_f32 v[90:91], v[90:91], v[90:91] op_sel:[0,1] op_sel_hi:[1,0]
	v_fmac_f32_e32 v109, v111, v118
	v_fmamk_f32 v91, v112, 0x3c088889, v239
	v_fmaak_f32 v91, v112, v91, 0x3e2aaaab
	v_fma_f32 v91, v112, v91, 0.5
	v_fma_f32 v91, v112, v91, 1.0
	v_mul_f32_e64 v91, v91, -v112
	v_fma_f32 v107, -v107, v107, 1.0
	v_cndmask_b32_e32 v91, v107, v91, vcc
	v_max_f32_e32 v91, 0, v91
	v_sqrt_f32_e32 v91, v91
	ds_bpermute_b32 v110, v50, v109
	ds_bpermute_b32 v114, v51, v109
	ds_bpermute_b32 v118, v52, v109
	v_mul_f32_e32 v86, v86, v91
	v_cvt_pk_bf16_f32 v86, v93, v86
	v_add_f32_e32 v93, v56, v115
	v_mul_f32_e32 v93, 0xbfb8aa3b, v93
	v_exp_f32_e32 v93, v93
	ds_bpermute_b32 v120, v53, v109
	v_exp_f32_e32 v89, v89
	v_lshlrev_b32_e32 v91, 16, v86
	v_add_f32_e32 v93, 1.0, v93
	v_rcp_f32_e64 v93, -v93
	v_add_f32_e32 v89, 1.0, v89
	v_rcp_f32_e32 v89, v89
	v_exp_f32_e32 v108, v91
	v_mul_f32_e32 v93, v40, v93
	v_add_f32_e32 v95, v93, v93
	v_mul_f32_e32 v93, 0x3fb8aa3b, v93
	v_fmamk_f32 v107, v95, 0x3c088889, v239
	v_exp_f32_e32 v109, v93
	v_fmaak_f32 v107, v95, v107, 0x3e2aaaab
	v_fma_f32 v107, v95, v107, 0.5
	v_fma_f32 v107, v95, v107, 1.0
	v_mul_f32_e64 v107, v107, -v95
	v_cmp_lt_f32_e32 vcc, s80, v95
	v_fma_f32 v95, -v109, v109, 1.0
	v_mul_f32_e32 v89, v89, v123
	v_cndmask_b32_e32 v95, v95, v107, vcc
	v_max_f32_e32 v95, 0, v95
	v_sqrt_f32_e32 v95, v95
	v_and_b32_e32 v91, 0xffff0000, v86
	ds_bpermute_b32 v92, v50, v90
	ds_bpermute_b32 v94, v51, v90
	v_mul_f32_e32 v87, v95, v87
	v_add_f32_e32 v95, v56, v116
	v_mul_f32_e32 v95, 0xbfb8aa3b, v95
	v_exp_f32_e32 v95, v95
	v_cvt_pk_bf16_f32 v87, v93, v87
	ds_bpermute_b32 v106, v52, v90
	v_lshlrev_b32_e32 v93, 16, v87
	v_add_f32_e32 v95, 1.0, v95
	v_rcp_f32_e64 v95, -v95
	v_exp_f32_e32 v112, v93
	v_and_b32_e32 v93, 0xffff0000, v87
	ds_bpermute_b32 v90, v53, v90
	v_mul_f32_e32 v95, v40, v95
	v_add_f32_e32 v107, v95, v95
	v_mul_f32_e32 v95, 0x3fb8aa3b, v95
	v_fmamk_f32 v109, v107, 0x3c088889, v239
	v_exp_f32_e32 v111, v95
	v_fmaak_f32 v109, v107, v109, 0x3e2aaaab
	v_fma_f32 v109, v107, v109, 0.5
	v_fma_f32 v109, v107, v109, 1.0
	v_mul_f32_e64 v109, v109, -v107
	v_cmp_lt_f32_e32 vcc, s80, v107
	v_fma_f32 v107, -v111, v111, 1.0
	v_fmac_f32_e32 v93, v112, v91
	v_cndmask_b32_e32 v107, v107, v109, vcc
	v_max_f32_e32 v107, 0, v107
	v_sqrt_f32_e32 v107, v107
	s_nop 0
	v_mul_f32_e32 v88, v107, v88
	v_add_f32_e32 v107, v56, v117
	v_mul_f32_e32 v107, 0xbfb8aa3b, v107
	v_exp_f32_e32 v107, v107
	v_cvt_pk_bf16_f32 v88, v95, v88
	s_nop 0
	v_lshlrev_b32_e32 v95, 16, v88
	v_add_f32_e32 v107, 1.0, v107
	v_rcp_f32_e64 v107, -v107
	v_exp_f32_e32 v109, v95
	v_and_b32_e32 v95, 0xffff0000, v88
	v_mul_f32_e32 v107, v40, v107
	v_add_f32_e32 v111, v107, v107
	v_mul_f32_e32 v107, 0x3fb8aa3b, v107
	v_fmamk_f32 v113, v111, 0x3c088889, v239
	v_exp_f32_e32 v115, v107
	v_fmaak_f32 v113, v111, v113, 0x3e2aaaab
	v_fma_f32 v113, v111, v113, 0.5
	v_fma_f32 v113, v111, v113, 1.0
	v_mul_f32_e64 v113, v113, -v111
	v_cmp_lt_f32_e32 vcc, s80, v111
	v_fma_f32 v111, -v115, v115, 1.0
	v_fmac_f32_e32 v95, v109, v93
	v_cndmask_b32_e32 v111, v111, v113, vcc
	v_max_f32_e32 v111, 0, v111
	v_sqrt_f32_e32 v111, v111
	s_nop 0
	v_mul_f32_e32 v89, v111, v89
	v_cvt_pk_bf16_f32 v89, v107, v89
	global_store_dwordx4 v[42:43], v[86:89], off offset:1024
	v_lshlrev_b32_e32 v107, 16, v89
	v_exp_f32_e32 v113, v107
	v_and_b32_e32 v116, 0xffff0000, v89
	v_lshl_add_u64 v[42:43], v[42:43], 0, s[78:79]
	v_pk_mul_f32 v[86:87], v[108:109], v[112:113]
	s_nop 0
	v_pk_mul_f32 v[86:87], v[86:87], v[86:87] op_sel:[0,1] op_sel_hi:[1,0]
	v_fmac_f32_e32 v116, v113, v95
	ds_bpermute_b32 v93, v50, v86
	ds_bpermute_b32 v111, v50, v116
	ds_bpermute_b32 v95, v51, v86
	ds_bpermute_b32 v107, v52, v86
	ds_bpermute_b32 v91, v53, v86
	ds_bpermute_b32 v115, v51, v116
	ds_bpermute_b32 v119, v52, v116
	ds_bpermute_b32 v121, v53, v116
	s_waitcnt lgkmcnt(6)
	v_pk_fma_f32 v[34:35], v[34:35], v[92:93], v[110:111]
	s_waitcnt lgkmcnt(5)
	v_pk_mul_f32 v[86:87], v[92:93], v[94:95]
	s_waitcnt lgkmcnt(2)
	v_pk_fma_f32 v[34:35], v[34:35], v[94:95], v[114:115]
	v_pk_mul_f32 v[88:89], v[106:107], v[90:91]
	s_waitcnt lgkmcnt(1)
	v_pk_fma_f32 v[34:35], v[34:35], v[106:107], v[118:119]
	v_pk_mul_f32 v[86:87], v[86:87], v[88:89]
	s_waitcnt lgkmcnt(0)
	v_pk_fma_f32 v[34:35], v[34:35], v[90:91], v[120:121]
	v_pk_mul_f32 v[38:39], v[38:39], v[86:87]
	v_mov_b32_e32 v95, v105
	v_mov_b32_e32 v94, v104
	v_mov_b32_e32 v93, v103
	v_mov_b32_e32 v91, v102
	v_mov_b32_e32 v92, v101
	v_mov_b32_e32 v90, v100
	v_mov_b32_e32 v89, v99
	v_mov_b32_e32 v87, v98
	v_mov_b32_e32 v88, v97
	v_mov_b32_e32 v86, v96
	v_mov_b32_e32 v111, v85
	v_mov_b32_e32 v109, v84
	v_mov_b32_e32 v110, v83
	v_mov_b32_e32 v108, v82
	v_mov_b32_e32 v106, v81
	v_mov_b32_e32 v107, v80
	s_cbranch_scc0 .LBB0_467
	v_cmp_gt_u32_e64 s[0:1], 16, v32
	s_and_saveexec_b64 s[16:17], s[0:1]
	s_cbranch_execz .LBB0_470
	s_and_b32 s3, s3, 0x3fffffc0
	s_lshl_b32 s3, s3, 2
	s_add_i32 s3, s3, 0
	v_lshl_add_u32 v0, v44, 2, s3
	v_add_u32_e32 v0, 0x9000, v0
	ds_write2_b32 v0, v38, v39 offset1:16
	ds_write2_b32 v0, v34, v35 offset0:32 offset1:48
